# P1 QKV epilogue rewritten by hand: tile-uniform decisions hoisted to scalar code, SGPR address increments, half the instruction count
# baseline (speedup 1.0000x reference)
.LBB0_147:
	s_ashr_i32 s8, s6, 1
	s_cmp_gt_i32 s8, 2
	s_cselect_b32 s4, 1, 0
	s_mul_i32 s5, s4, 3
	s_sub_i32 s9, s8, s5
	s_and_b32 s7, s6, 1
	s_lshl_b32 s7, s7, 2
	s_or_b32 s71, s7, s35
	s_lshl_b32 s5, s4, 1
	s_add_i32 s5, s5, s9
	s_lshl_b32 s12, s5, 8
	s_mov_b32 s13, 0
	s_cmp_eq_u32 s9, 0
	s_cselect_b32 s45, 0x3e38aa3b, 1.0
	v_xor_b32_e32 v176, 16, v193
	v_lshlrev_b32_e32 v176, 2, v176
	v_xor_b32_e32 v177, 32, v193
	v_lshlrev_b32_e32 v177, 2, v177
	v_mov_b32_e32 v195, 0
	v_mov_b32_e32 v199, 0
	s_mov_b32 s37, 0
	s_mov_b32 s51, 0
	s_mov_b64 s[36:37], 0x8000
	s_mov_b64 s[50:51], 0x28000
	s_cmpk_lt_i32 s14, 0x100
	s_cbranch_scc0 .Lq_sample
	s_lshr_b32 s20, s14, 3
	s_and_b32 s21, s14, 7
	s_lshl_b32 s22, s20, 3
	s_add_i32 s22, s22, s71
	s_lshl_b32 s22, s22, 11
	s_lshl_b32 s23, s21, 8
	s_add_i32 s22, s22, s23
	s_lshl_b32 s22, s22, 7
	s_lshl_b32 s23, s8, 26
	s_add_u32 s22, s22, s23
	s_add_u32 s72, s54, s22
	s_addc_u32 s73, s55, 0
	s_cmp_eq_u32 s4, 1
	s_cbranch_scc0 .Lq_pA
	s_lshl_b32 s22, s20, 11
	s_lshl_b32 s23, s21, 8
	s_add_i32 s22, s22, s23
	s_cmp_eq_u32 s9, 1
	s_mov_b32 s23, 0x1c400000
	s_cselect_b32 s23, 0x14400000, s23
	s_mov_b64 s[20:21], -1
	s_branch .Lq_pF
.Lq_pA:
	s_lshl_b32 s22, s20, 9
	s_add_i32 s23, s21, -6
	s_lshl_b32 s23, s23, 8
	s_add_i32 s22, s22, s23
	s_cmp_gt_u32 s21, 5
	s_cselect_b64 s[20:21], -1, 0
	s_cmp_eq_u32 s9, 1
	s_mov_b32 s23, 0x12400000
	s_cselect_b32 s23, 0x10400000, s23
.Lq_pF:
	s_lshl_b32 s22, s22, 3
	s_add_i32 s22, s22, s71
	s_lshl_b32 s22, s22, 8
	s_add_u32 s22, s22, s23
	s_add_u32 s74, s10, s22
	s_addc_u32 s75, s11, 0
	s_cmp_eq_u32 s9, 0
	s_cselect_b64 s[22:23], 0, -1
	s_and_b64 s[20:21], s[20:21], s[22:23]
	v_lshlrev_b32_e32 v194, 7, v141
	v_lshl_add_u32 v194, v138, 1, v194
	v_lshlrev_b32_e32 v198, 11, v141
	v_lshl_add_u32 v198, v138, 2, v198
	s_mov_b64 s[76:77], 0x800
	s_mov_b64 s[78:79], 0x800
	s_mov_b64 s[70:71], 0x2800
	s_branch .Lq_addr
.Lq_sample:
	s_add_i32 s20, s14, 0xffffff00
	s_lshl_b32 s20, s20, 3
	s_lshl_b32 s22, s20, 15
	s_lshl_b32 s23, s71, 12
	s_add_i32 s22, s22, s23
	s_lshl_b32 s23, s4, 21
	s_lshl_b32 s21, s9, 20
	s_add_i32 s23, s23, s21
	s_add_u32 s23, s23, 0x2ce00000
	s_lshl_b32 s21, s4, 20
	s_add_u32 s21, s21, 0x2cd00000
	s_cmp_eq_u32 s9, 0
	s_cselect_b32 s23, s21, s23
	s_add_u32 s22, s22, s23
	s_add_u32 s72, s84, s22
	s_addc_u32 s73, s85, 0
	s_lshl_b32 s22, s20, 16
	s_lshl_b32 s23, s71, 8
	s_add_i32 s22, s22, s23
	s_add_i32 s23, s9, -1
	s_lshl_b32 s23, s23, 21
	s_lshl_b32 s21, s4, 22
	s_add_i32 s23, s23, s21
	s_add_u32 s23, s23, 0x24600000
	s_add_u32 s22, s22, s23
	s_add_u32 s74, s10, s22
	s_addc_u32 s75, s11, 0
	s_cmp_eq_u32 s9, 0
	s_cselect_b64 s[20:21], 0, -1
	v_lshrrev_b32_e32 v196, 6, v141
	v_and_b32_e32 v197, 15, v141
	v_lshlrev_b32_e32 v194, 16, v196
	v_lshl_add_u32 v194, v197, 7, v194
	v_lshl_add_u32 v194, v138, 1, v194
	v_lshlrev_b32_e32 v198, 17, v196
	v_lshl_add_u32 v198, v197, 11, v198
	v_lshl_add_u32 v198, v138, 2, v198
	s_mov_b64 s[76:77], 0x800
	s_mov_b64 s[78:79], 0x7800
	s_mov_b64 s[70:71], 0x17800
.Lq_addr:
	v_lshl_add_u64 v[196:197], s[72:73], 0, v[194:195]
	v_lshl_add_u64 v[200:201], s[74:75], 0, v[198:199]
	s_cmp_eq_u32 s9, 2
	s_cbranch_scc1 .Lq_nonorm
	v_lshl_add_u64 v[178:179], v[142:143], 0, s[12:13]
	global_load_dwordx4 v[152:155], v[178:179], off
	global_load_dwordx4 v[156:159], v[178:179], off offset:16
	global_load_dwordx4 v[160:163], v[178:179], off offset:128
	global_load_dwordx4 v[164:167], v[178:179], off offset:144
	s_waitcnt vmcnt(0)
	v_mul_f32_e32 v152, s45, v152
	v_mul_f32_e32 v153, s45, v153
	v_mul_f32_e32 v154, s45, v154
	v_mul_f32_e32 v155, s45, v155
	v_mul_f32_e32 v156, s45, v156
	v_mul_f32_e32 v157, s45, v157
	v_mul_f32_e32 v158, s45, v158
	v_mul_f32_e32 v159, s45, v159
	v_mul_f32_e32 v160, s45, v160
	v_mul_f32_e32 v161, s45, v161
	v_mul_f32_e32 v162, s45, v162
	v_mul_f32_e32 v163, s45, v163
	v_mul_f32_e32 v164, s45, v164
	v_mul_f32_e32 v165, s45, v165
	v_mul_f32_e32 v166, s45, v166
	v_mul_f32_e32 v167, s45, v167
	v_mov_b32_e32 v136, v240
	v_pk_mul_f32 v[124:125], v[124:125], v[136:137] op_sel_hi:[1,0]
	v_pk_mul_f32 v[126:127], v[126:127], v[136:137] op_sel_hi:[1,0]
	v_pk_mul_f32 v[120:121], v[120:121], v[136:137] op_sel_hi:[1,0]
	v_pk_mul_f32 v[122:123], v[122:123], v[136:137] op_sel_hi:[1,0]
	v_pk_mul_f32 v[116:117], v[116:117], v[136:137] op_sel_hi:[1,0]
	v_pk_mul_f32 v[118:119], v[118:119], v[136:137] op_sel_hi:[1,0]
	v_pk_mul_f32 v[112:113], v[112:113], v[136:137] op_sel_hi:[1,0]
	v_pk_mul_f32 v[114:115], v[114:115], v[136:137] op_sel_hi:[1,0]
	v_mul_f32_e32 v168, v125, v125
	v_mul_f32_e32 v169, v127, v127
	v_mul_f32_e32 v170, v121, v121
	v_mul_f32_e32 v171, v123, v123
	v_mul_f32_e32 v172, v117, v117
	v_mul_f32_e32 v173, v119, v119
	v_mul_f32_e32 v174, v113, v113
	v_mul_f32_e32 v175, v115, v115
	v_fmac_f32_e32 v168, v124, v124
	v_fmac_f32_e32 v169, v126, v126
	v_fmac_f32_e32 v170, v120, v120
	v_fmac_f32_e32 v171, v122, v122
	v_fmac_f32_e32 v172, v116, v116
	v_fmac_f32_e32 v173, v118, v118
	v_fmac_f32_e32 v174, v112, v112
	v_fmac_f32_e32 v175, v114, v114
	v_add_f32_e32 v168, v168, v169
	v_add_f32_e32 v170, v170, v171
	v_add_f32_e32 v172, v172, v173
	v_add_f32_e32 v174, v174, v175
	v_add_f32_e32 v168, v168, v170
	v_add_f32_e32 v168, v168, v172
	v_add_f32_e32 v168, v168, v174
	ds_bpermute_b32 v169, v176, v168
	s_waitcnt lgkmcnt(0)
	v_add_f32_e32 v168, v168, v169
	ds_bpermute_b32 v169, v177, v168
	s_waitcnt lgkmcnt(0)
	v_add_f32_e32 v168, v168, v169
	v_fmamk_f32 v168, v168, 0x3c800000, v191
	v_rsq_f32_e32 v136, v168
	s_nop 0
	v_pk_mul_f32 v[124:125], v[124:125], v[136:137] op_sel_hi:[1,0]
	v_pk_mul_f32 v[126:127], v[126:127], v[136:137] op_sel_hi:[1,0]
	v_pk_mul_f32 v[120:121], v[120:121], v[136:137] op_sel_hi:[1,0]
	v_pk_mul_f32 v[122:123], v[122:123], v[136:137] op_sel_hi:[1,0]
	v_pk_mul_f32 v[116:117], v[116:117], v[136:137] op_sel_hi:[1,0]
	v_pk_mul_f32 v[118:119], v[118:119], v[136:137] op_sel_hi:[1,0]
	v_pk_mul_f32 v[112:113], v[112:113], v[136:137] op_sel_hi:[1,0]
	v_pk_mul_f32 v[114:115], v[114:115], v[136:137] op_sel_hi:[1,0]
	v_pk_mul_f32 v[124:125], v[152:153], v[124:125]
	v_pk_mul_f32 v[126:127], v[154:155], v[126:127]
	v_pk_mul_f32 v[120:121], v[156:157], v[120:121]
	v_pk_mul_f32 v[122:123], v[158:159], v[122:123]
	v_pk_mul_f32 v[116:117], v[160:161], v[116:117]
	v_pk_mul_f32 v[118:119], v[162:163], v[118:119]
	v_pk_mul_f32 v[112:113], v[164:165], v[112:113]
	v_pk_mul_f32 v[114:115], v[166:167], v[114:115]
	v_cvt_pk_bf16_f32 v208, v124, v125
	v_cvt_pk_bf16_f32 v209, v126, v127
	v_cvt_pk_bf16_f32 v210, v120, v121
	v_cvt_pk_bf16_f32 v211, v122, v123
	v_cvt_pk_bf16_f32 v212, v116, v117
	v_cvt_pk_bf16_f32 v213, v118, v119
	v_cvt_pk_bf16_f32 v214, v112, v113
	v_cvt_pk_bf16_f32 v215, v114, v115
	global_store_dwordx4 v[196:197], v[208:211], off
	global_store_dwordx4 v[196:197], v[212:215], off offset:64
	s_and_b64 vcc, exec, s[20:21]
	s_cbranch_vccz .Lq_nf_n0
	global_store_dwordx4 v[200:201], v[124:127], off nt
	global_store_dwordx4 v[200:201], v[120:123], off offset:16 nt
	global_store_dwordx4 v[200:201], v[116:119], off offset:128 nt
	global_store_dwordx4 v[200:201], v[112:115], off offset:144 nt
.Lq_nf_n0:
	v_lshl_add_u64 v[196:197], v[196:197], 0, s[76:77]
	v_lshl_add_u64 v[200:201], v[200:201], 0, s[36:37]
	v_mov_b32_e32 v136, v241
	v_pk_mul_f32 v[108:109], v[108:109], v[136:137] op_sel_hi:[1,0]
	v_pk_mul_f32 v[110:111], v[110:111], v[136:137] op_sel_hi:[1,0]
	v_pk_mul_f32 v[104:105], v[104:105], v[136:137] op_sel_hi:[1,0]
	v_pk_mul_f32 v[106:107], v[106:107], v[136:137] op_sel_hi:[1,0]
	v_pk_mul_f32 v[100:101], v[100:101], v[136:137] op_sel_hi:[1,0]
	v_pk_mul_f32 v[102:103], v[102:103], v[136:137] op_sel_hi:[1,0]
	v_pk_mul_f32 v[96:97], v[96:97], v[136:137] op_sel_hi:[1,0]
	v_pk_mul_f32 v[98:99], v[98:99], v[136:137] op_sel_hi:[1,0]
	v_mul_f32_e32 v168, v109, v109
	v_mul_f32_e32 v169, v111, v111
	v_mul_f32_e32 v170, v105, v105
	v_mul_f32_e32 v171, v107, v107
	v_mul_f32_e32 v172, v101, v101
	v_mul_f32_e32 v173, v103, v103
	v_mul_f32_e32 v174, v97, v97
	v_mul_f32_e32 v175, v99, v99
	v_fmac_f32_e32 v168, v108, v108
	v_fmac_f32_e32 v169, v110, v110
	v_fmac_f32_e32 v170, v104, v104
	v_fmac_f32_e32 v171, v106, v106
	v_fmac_f32_e32 v172, v100, v100
	v_fmac_f32_e32 v173, v102, v102
	v_fmac_f32_e32 v174, v96, v96
	v_fmac_f32_e32 v175, v98, v98
	v_add_f32_e32 v168, v168, v169
	v_add_f32_e32 v170, v170, v171
	v_add_f32_e32 v172, v172, v173
	v_add_f32_e32 v174, v174, v175
	v_add_f32_e32 v168, v168, v170
	v_add_f32_e32 v168, v168, v172
	v_add_f32_e32 v168, v168, v174
	ds_bpermute_b32 v169, v176, v168
	s_waitcnt lgkmcnt(0)
	v_add_f32_e32 v168, v168, v169
	ds_bpermute_b32 v169, v177, v168
	s_waitcnt lgkmcnt(0)
	v_add_f32_e32 v168, v168, v169
	v_fmamk_f32 v168, v168, 0x3c800000, v191
	v_rsq_f32_e32 v136, v168
	s_nop 0
	v_pk_mul_f32 v[108:109], v[108:109], v[136:137] op_sel_hi:[1,0]
	v_pk_mul_f32 v[110:111], v[110:111], v[136:137] op_sel_hi:[1,0]
	v_pk_mul_f32 v[104:105], v[104:105], v[136:137] op_sel_hi:[1,0]
	v_pk_mul_f32 v[106:107], v[106:107], v[136:137] op_sel_hi:[1,0]
	v_pk_mul_f32 v[100:101], v[100:101], v[136:137] op_sel_hi:[1,0]
	v_pk_mul_f32 v[102:103], v[102:103], v[136:137] op_sel_hi:[1,0]
	v_pk_mul_f32 v[96:97], v[96:97], v[136:137] op_sel_hi:[1,0]
	v_pk_mul_f32 v[98:99], v[98:99], v[136:137] op_sel_hi:[1,0]
	v_pk_mul_f32 v[108:109], v[152:153], v[108:109]
	v_pk_mul_f32 v[110:111], v[154:155], v[110:111]
	v_pk_mul_f32 v[104:105], v[156:157], v[104:105]
	v_pk_mul_f32 v[106:107], v[158:159], v[106:107]
	v_pk_mul_f32 v[100:101], v[160:161], v[100:101]
	v_pk_mul_f32 v[102:103], v[162:163], v[102:103]
	v_pk_mul_f32 v[96:97], v[164:165], v[96:97]
	v_pk_mul_f32 v[98:99], v[166:167], v[98:99]
	v_cvt_pk_bf16_f32 v208, v108, v109
	v_cvt_pk_bf16_f32 v209, v110, v111
	v_cvt_pk_bf16_f32 v210, v104, v105
	v_cvt_pk_bf16_f32 v211, v106, v107
	v_cvt_pk_bf16_f32 v212, v100, v101
	v_cvt_pk_bf16_f32 v213, v102, v103
	v_cvt_pk_bf16_f32 v214, v96, v97
	v_cvt_pk_bf16_f32 v215, v98, v99
	global_store_dwordx4 v[196:197], v[208:211], off
	global_store_dwordx4 v[196:197], v[212:215], off offset:64
	s_and_b64 vcc, exec, s[20:21]
	s_cbranch_vccz .Lq_nf_n1
	global_store_dwordx4 v[200:201], v[108:111], off nt
	global_store_dwordx4 v[200:201], v[104:107], off offset:16 nt
	global_store_dwordx4 v[200:201], v[100:103], off offset:128 nt
	global_store_dwordx4 v[200:201], v[96:99], off offset:144 nt
.Lq_nf_n1:
	v_lshl_add_u64 v[196:197], v[196:197], 0, s[78:79]
	v_lshl_add_u64 v[200:201], v[200:201], 0, s[36:37]
	v_mov_b32_e32 v136, v242
	v_pk_mul_f32 v[92:93], v[92:93], v[136:137] op_sel_hi:[1,0]
	v_pk_mul_f32 v[94:95], v[94:95], v[136:137] op_sel_hi:[1,0]
	v_pk_mul_f32 v[88:89], v[88:89], v[136:137] op_sel_hi:[1,0]
	v_pk_mul_f32 v[90:91], v[90:91], v[136:137] op_sel_hi:[1,0]
	v_pk_mul_f32 v[84:85], v[84:85], v[136:137] op_sel_hi:[1,0]
	v_pk_mul_f32 v[86:87], v[86:87], v[136:137] op_sel_hi:[1,0]
	v_pk_mul_f32 v[80:81], v[80:81], v[136:137] op_sel_hi:[1,0]
	v_pk_mul_f32 v[82:83], v[82:83], v[136:137] op_sel_hi:[1,0]
	v_mul_f32_e32 v168, v93, v93
	v_mul_f32_e32 v169, v95, v95
	v_mul_f32_e32 v170, v89, v89
	v_mul_f32_e32 v171, v91, v91
	v_mul_f32_e32 v172, v85, v85
	v_mul_f32_e32 v173, v87, v87
	v_mul_f32_e32 v174, v81, v81
	v_mul_f32_e32 v175, v83, v83
	v_fmac_f32_e32 v168, v92, v92
	v_fmac_f32_e32 v169, v94, v94
	v_fmac_f32_e32 v170, v88, v88
	v_fmac_f32_e32 v171, v90, v90
	v_fmac_f32_e32 v172, v84, v84
	v_fmac_f32_e32 v173, v86, v86
	v_fmac_f32_e32 v174, v80, v80
	v_fmac_f32_e32 v175, v82, v82
	v_add_f32_e32 v168, v168, v169
	v_add_f32_e32 v170, v170, v171
	v_add_f32_e32 v172, v172, v173
	v_add_f32_e32 v174, v174, v175
	v_add_f32_e32 v168, v168, v170
	v_add_f32_e32 v168, v168, v172
	v_add_f32_e32 v168, v168, v174
	ds_bpermute_b32 v169, v176, v168
	s_waitcnt lgkmcnt(0)
	v_add_f32_e32 v168, v168, v169
	ds_bpermute_b32 v169, v177, v168
	s_waitcnt lgkmcnt(0)
	v_add_f32_e32 v168, v168, v169
	v_fmamk_f32 v168, v168, 0x3c800000, v191
	v_rsq_f32_e32 v136, v168
	s_nop 0
	v_pk_mul_f32 v[92:93], v[92:93], v[136:137] op_sel_hi:[1,0]
	v_pk_mul_f32 v[94:95], v[94:95], v[136:137] op_sel_hi:[1,0]
	v_pk_mul_f32 v[88:89], v[88:89], v[136:137] op_sel_hi:[1,0]
	v_pk_mul_f32 v[90:91], v[90:91], v[136:137] op_sel_hi:[1,0]
	v_pk_mul_f32 v[84:85], v[84:85], v[136:137] op_sel_hi:[1,0]
	v_pk_mul_f32 v[86:87], v[86:87], v[136:137] op_sel_hi:[1,0]
	v_pk_mul_f32 v[80:81], v[80:81], v[136:137] op_sel_hi:[1,0]
	v_pk_mul_f32 v[82:83], v[82:83], v[136:137] op_sel_hi:[1,0]
	v_pk_mul_f32 v[92:93], v[152:153], v[92:93]
	v_pk_mul_f32 v[94:95], v[154:155], v[94:95]
	v_pk_mul_f32 v[88:89], v[156:157], v[88:89]
	v_pk_mul_f32 v[90:91], v[158:159], v[90:91]
	v_pk_mul_f32 v[84:85], v[160:161], v[84:85]
	v_pk_mul_f32 v[86:87], v[162:163], v[86:87]
	v_pk_mul_f32 v[80:81], v[164:165], v[80:81]
	v_pk_mul_f32 v[82:83], v[166:167], v[82:83]
	v_cvt_pk_bf16_f32 v208, v92, v93
	v_cvt_pk_bf16_f32 v209, v94, v95
	v_cvt_pk_bf16_f32 v210, v88, v89
	v_cvt_pk_bf16_f32 v211, v90, v91
	v_cvt_pk_bf16_f32 v212, v84, v85
	v_cvt_pk_bf16_f32 v213, v86, v87
	v_cvt_pk_bf16_f32 v214, v80, v81
	v_cvt_pk_bf16_f32 v215, v82, v83
	global_store_dwordx4 v[196:197], v[208:211], off
	global_store_dwordx4 v[196:197], v[212:215], off offset:64
	s_and_b64 vcc, exec, s[20:21]
	s_cbranch_vccz .Lq_nf_n2
	global_store_dwordx4 v[200:201], v[92:95], off nt
	global_store_dwordx4 v[200:201], v[88:91], off offset:16 nt
	global_store_dwordx4 v[200:201], v[84:87], off offset:128 nt
	global_store_dwordx4 v[200:201], v[80:83], off offset:144 nt
.Lq_nf_n2:
	v_lshl_add_u64 v[196:197], v[196:197], 0, s[76:77]
	v_lshl_add_u64 v[200:201], v[200:201], 0, s[36:37]
	v_mov_b32_e32 v136, v243
	v_pk_mul_f32 v[76:77], v[76:77], v[136:137] op_sel_hi:[1,0]
	v_pk_mul_f32 v[78:79], v[78:79], v[136:137] op_sel_hi:[1,0]
	v_pk_mul_f32 v[72:73], v[72:73], v[136:137] op_sel_hi:[1,0]
	v_pk_mul_f32 v[74:75], v[74:75], v[136:137] op_sel_hi:[1,0]
	v_pk_mul_f32 v[68:69], v[68:69], v[136:137] op_sel_hi:[1,0]
	v_pk_mul_f32 v[70:71], v[70:71], v[136:137] op_sel_hi:[1,0]
	v_pk_mul_f32 v[64:65], v[64:65], v[136:137] op_sel_hi:[1,0]
	v_pk_mul_f32 v[66:67], v[66:67], v[136:137] op_sel_hi:[1,0]
	v_mul_f32_e32 v168, v77, v77
	v_mul_f32_e32 v169, v79, v79
	v_mul_f32_e32 v170, v73, v73
	v_mul_f32_e32 v171, v75, v75
	v_mul_f32_e32 v172, v69, v69
	v_mul_f32_e32 v173, v71, v71
	v_mul_f32_e32 v174, v65, v65
	v_mul_f32_e32 v175, v67, v67
	v_fmac_f32_e32 v168, v76, v76
	v_fmac_f32_e32 v169, v78, v78
	v_fmac_f32_e32 v170, v72, v72
	v_fmac_f32_e32 v171, v74, v74
	v_fmac_f32_e32 v172, v68, v68
	v_fmac_f32_e32 v173, v70, v70
	v_fmac_f32_e32 v174, v64, v64
	v_fmac_f32_e32 v175, v66, v66
	v_add_f32_e32 v168, v168, v169
	v_add_f32_e32 v170, v170, v171
	v_add_f32_e32 v172, v172, v173
	v_add_f32_e32 v174, v174, v175
	v_add_f32_e32 v168, v168, v170
	v_add_f32_e32 v168, v168, v172
	v_add_f32_e32 v168, v168, v174
	ds_bpermute_b32 v169, v176, v168
	s_waitcnt lgkmcnt(0)
	v_add_f32_e32 v168, v168, v169
	ds_bpermute_b32 v169, v177, v168
	s_waitcnt lgkmcnt(0)
	v_add_f32_e32 v168, v168, v169
	v_fmamk_f32 v168, v168, 0x3c800000, v191
	v_rsq_f32_e32 v136, v168
	s_nop 0
	v_pk_mul_f32 v[76:77], v[76:77], v[136:137] op_sel_hi:[1,0]
	v_pk_mul_f32 v[78:79], v[78:79], v[136:137] op_sel_hi:[1,0]
	v_pk_mul_f32 v[72:73], v[72:73], v[136:137] op_sel_hi:[1,0]
	v_pk_mul_f32 v[74:75], v[74:75], v[136:137] op_sel_hi:[1,0]
	v_pk_mul_f32 v[68:69], v[68:69], v[136:137] op_sel_hi:[1,0]
	v_pk_mul_f32 v[70:71], v[70:71], v[136:137] op_sel_hi:[1,0]
	v_pk_mul_f32 v[64:65], v[64:65], v[136:137] op_sel_hi:[1,0]
	v_pk_mul_f32 v[66:67], v[66:67], v[136:137] op_sel_hi:[1,0]
	v_pk_mul_f32 v[76:77], v[152:153], v[76:77]
	v_pk_mul_f32 v[78:79], v[154:155], v[78:79]
	v_pk_mul_f32 v[72:73], v[156:157], v[72:73]
	v_pk_mul_f32 v[74:75], v[158:159], v[74:75]
	v_pk_mul_f32 v[68:69], v[160:161], v[68:69]
	v_pk_mul_f32 v[70:71], v[162:163], v[70:71]
	v_pk_mul_f32 v[64:65], v[164:165], v[64:65]
	v_pk_mul_f32 v[66:67], v[166:167], v[66:67]
	v_cvt_pk_bf16_f32 v208, v76, v77
	v_cvt_pk_bf16_f32 v209, v78, v79
	v_cvt_pk_bf16_f32 v210, v72, v73
	v_cvt_pk_bf16_f32 v211, v74, v75
	v_cvt_pk_bf16_f32 v212, v68, v69
	v_cvt_pk_bf16_f32 v213, v70, v71
	v_cvt_pk_bf16_f32 v214, v64, v65
	v_cvt_pk_bf16_f32 v215, v66, v67
	global_store_dwordx4 v[196:197], v[208:211], off
	global_store_dwordx4 v[196:197], v[212:215], off offset:64
	s_and_b64 vcc, exec, s[20:21]
	s_cbranch_vccz .Lq_nf_n3
	global_store_dwordx4 v[200:201], v[76:79], off nt
	global_store_dwordx4 v[200:201], v[72:75], off offset:16 nt
	global_store_dwordx4 v[200:201], v[68:71], off offset:128 nt
	global_store_dwordx4 v[200:201], v[64:67], off offset:144 nt
.Lq_nf_n3:
	v_lshl_add_u64 v[196:197], v[196:197], 0, s[70:71]
	v_lshl_add_u64 v[200:201], v[200:201], 0, s[50:51]
	v_mov_b32_e32 v136, v244
	v_pk_mul_f32 v[60:61], v[60:61], v[136:137] op_sel_hi:[1,0]
	v_pk_mul_f32 v[62:63], v[62:63], v[136:137] op_sel_hi:[1,0]
	v_pk_mul_f32 v[56:57], v[56:57], v[136:137] op_sel_hi:[1,0]
	v_pk_mul_f32 v[58:59], v[58:59], v[136:137] op_sel_hi:[1,0]
	v_pk_mul_f32 v[52:53], v[52:53], v[136:137] op_sel_hi:[1,0]
	v_pk_mul_f32 v[54:55], v[54:55], v[136:137] op_sel_hi:[1,0]
	v_pk_mul_f32 v[48:49], v[48:49], v[136:137] op_sel_hi:[1,0]
	v_pk_mul_f32 v[50:51], v[50:51], v[136:137] op_sel_hi:[1,0]
	v_mul_f32_e32 v168, v61, v61
	v_mul_f32_e32 v169, v63, v63
	v_mul_f32_e32 v170, v57, v57
	v_mul_f32_e32 v171, v59, v59
	v_mul_f32_e32 v172, v53, v53
	v_mul_f32_e32 v173, v55, v55
	v_mul_f32_e32 v174, v49, v49
	v_mul_f32_e32 v175, v51, v51
	v_fmac_f32_e32 v168, v60, v60
	v_fmac_f32_e32 v169, v62, v62
	v_fmac_f32_e32 v170, v56, v56
	v_fmac_f32_e32 v171, v58, v58
	v_fmac_f32_e32 v172, v52, v52
	v_fmac_f32_e32 v173, v54, v54
	v_fmac_f32_e32 v174, v48, v48
	v_fmac_f32_e32 v175, v50, v50
	v_add_f32_e32 v168, v168, v169
	v_add_f32_e32 v170, v170, v171
	v_add_f32_e32 v172, v172, v173
	v_add_f32_e32 v174, v174, v175
	v_add_f32_e32 v168, v168, v170
	v_add_f32_e32 v168, v168, v172
	v_add_f32_e32 v168, v168, v174
	ds_bpermute_b32 v169, v176, v168
	s_waitcnt lgkmcnt(0)
	v_add_f32_e32 v168, v168, v169
	ds_bpermute_b32 v169, v177, v168
	s_waitcnt lgkmcnt(0)
	v_add_f32_e32 v168, v168, v169
	v_fmamk_f32 v168, v168, 0x3c800000, v191
	v_rsq_f32_e32 v136, v168
	s_nop 0
	v_pk_mul_f32 v[60:61], v[60:61], v[136:137] op_sel_hi:[1,0]
	v_pk_mul_f32 v[62:63], v[62:63], v[136:137] op_sel_hi:[1,0]
	v_pk_mul_f32 v[56:57], v[56:57], v[136:137] op_sel_hi:[1,0]
	v_pk_mul_f32 v[58:59], v[58:59], v[136:137] op_sel_hi:[1,0]
	v_pk_mul_f32 v[52:53], v[52:53], v[136:137] op_sel_hi:[1,0]
	v_pk_mul_f32 v[54:55], v[54:55], v[136:137] op_sel_hi:[1,0]
	v_pk_mul_f32 v[48:49], v[48:49], v[136:137] op_sel_hi:[1,0]
	v_pk_mul_f32 v[50:51], v[50:51], v[136:137] op_sel_hi:[1,0]
	v_pk_mul_f32 v[60:61], v[152:153], v[60:61]
	v_pk_mul_f32 v[62:63], v[154:155], v[62:63]
	v_pk_mul_f32 v[56:57], v[156:157], v[56:57]
	v_pk_mul_f32 v[58:59], v[158:159], v[58:59]
	v_pk_mul_f32 v[52:53], v[160:161], v[52:53]
	v_pk_mul_f32 v[54:55], v[162:163], v[54:55]
	v_pk_mul_f32 v[48:49], v[164:165], v[48:49]
	v_pk_mul_f32 v[50:51], v[166:167], v[50:51]
	v_cvt_pk_bf16_f32 v208, v60, v61
	v_cvt_pk_bf16_f32 v209, v62, v63
	v_cvt_pk_bf16_f32 v210, v56, v57
	v_cvt_pk_bf16_f32 v211, v58, v59
	v_cvt_pk_bf16_f32 v212, v52, v53
	v_cvt_pk_bf16_f32 v213, v54, v55
	v_cvt_pk_bf16_f32 v214, v48, v49
	v_cvt_pk_bf16_f32 v215, v50, v51
	global_store_dwordx4 v[196:197], v[208:211], off
	global_store_dwordx4 v[196:197], v[212:215], off offset:64
	s_and_b64 vcc, exec, s[20:21]
	s_cbranch_vccz .Lq_nf_n4
	global_store_dwordx4 v[200:201], v[60:63], off nt
	global_store_dwordx4 v[200:201], v[56:59], off offset:16 nt
	global_store_dwordx4 v[200:201], v[52:55], off offset:128 nt
	global_store_dwordx4 v[200:201], v[48:51], off offset:144 nt
.Lq_nf_n4:
	v_lshl_add_u64 v[196:197], v[196:197], 0, s[76:77]
	v_lshl_add_u64 v[200:201], v[200:201], 0, s[36:37]
	v_mov_b32_e32 v136, v245
	v_pk_mul_f32 v[44:45], v[44:45], v[136:137] op_sel_hi:[1,0]
	v_pk_mul_f32 v[46:47], v[46:47], v[136:137] op_sel_hi:[1,0]
	v_pk_mul_f32 v[40:41], v[40:41], v[136:137] op_sel_hi:[1,0]
	v_pk_mul_f32 v[42:43], v[42:43], v[136:137] op_sel_hi:[1,0]
	v_pk_mul_f32 v[36:37], v[36:37], v[136:137] op_sel_hi:[1,0]
	v_pk_mul_f32 v[38:39], v[38:39], v[136:137] op_sel_hi:[1,0]
	v_pk_mul_f32 v[32:33], v[32:33], v[136:137] op_sel_hi:[1,0]
	v_pk_mul_f32 v[34:35], v[34:35], v[136:137] op_sel_hi:[1,0]
	v_mul_f32_e32 v168, v45, v45
	v_mul_f32_e32 v169, v47, v47
	v_mul_f32_e32 v170, v41, v41
	v_mul_f32_e32 v171, v43, v43
	v_mul_f32_e32 v172, v37, v37
	v_mul_f32_e32 v173, v39, v39
	v_mul_f32_e32 v174, v33, v33
	v_mul_f32_e32 v175, v35, v35
	v_fmac_f32_e32 v168, v44, v44
	v_fmac_f32_e32 v169, v46, v46
	v_fmac_f32_e32 v170, v40, v40
	v_fmac_f32_e32 v171, v42, v42
	v_fmac_f32_e32 v172, v36, v36
	v_fmac_f32_e32 v173, v38, v38
	v_fmac_f32_e32 v174, v32, v32
	v_fmac_f32_e32 v175, v34, v34
	v_add_f32_e32 v168, v168, v169
	v_add_f32_e32 v170, v170, v171
	v_add_f32_e32 v172, v172, v173
	v_add_f32_e32 v174, v174, v175
	v_add_f32_e32 v168, v168, v170
	v_add_f32_e32 v168, v168, v172
	v_add_f32_e32 v168, v168, v174
	ds_bpermute_b32 v169, v176, v168
	s_waitcnt lgkmcnt(0)
	v_add_f32_e32 v168, v168, v169
	ds_bpermute_b32 v169, v177, v168
	s_waitcnt lgkmcnt(0)
	v_add_f32_e32 v168, v168, v169
	v_fmamk_f32 v168, v168, 0x3c800000, v191
	v_rsq_f32_e32 v136, v168
	s_nop 0
	v_pk_mul_f32 v[44:45], v[44:45], v[136:137] op_sel_hi:[1,0]
	v_pk_mul_f32 v[46:47], v[46:47], v[136:137] op_sel_hi:[1,0]
	v_pk_mul_f32 v[40:41], v[40:41], v[136:137] op_sel_hi:[1,0]
	v_pk_mul_f32 v[42:43], v[42:43], v[136:137] op_sel_hi:[1,0]
	v_pk_mul_f32 v[36:37], v[36:37], v[136:137] op_sel_hi:[1,0]
	v_pk_mul_f32 v[38:39], v[38:39], v[136:137] op_sel_hi:[1,0]
	v_pk_mul_f32 v[32:33], v[32:33], v[136:137] op_sel_hi:[1,0]
	v_pk_mul_f32 v[34:35], v[34:35], v[136:137] op_sel_hi:[1,0]
	v_pk_mul_f32 v[44:45], v[152:153], v[44:45]
	v_pk_mul_f32 v[46:47], v[154:155], v[46:47]
	v_pk_mul_f32 v[40:41], v[156:157], v[40:41]
	v_pk_mul_f32 v[42:43], v[158:159], v[42:43]
	v_pk_mul_f32 v[36:37], v[160:161], v[36:37]
	v_pk_mul_f32 v[38:39], v[162:163], v[38:39]
	v_pk_mul_f32 v[32:33], v[164:165], v[32:33]
	v_pk_mul_f32 v[34:35], v[166:167], v[34:35]
	v_cvt_pk_bf16_f32 v208, v44, v45
	v_cvt_pk_bf16_f32 v209, v46, v47
	v_cvt_pk_bf16_f32 v210, v40, v41
	v_cvt_pk_bf16_f32 v211, v42, v43
	v_cvt_pk_bf16_f32 v212, v36, v37
	v_cvt_pk_bf16_f32 v213, v38, v39
	v_cvt_pk_bf16_f32 v214, v32, v33
	v_cvt_pk_bf16_f32 v215, v34, v35
	global_store_dwordx4 v[196:197], v[208:211], off
	global_store_dwordx4 v[196:197], v[212:215], off offset:64
	s_and_b64 vcc, exec, s[20:21]
	s_cbranch_vccz .Lq_nf_n5
	global_store_dwordx4 v[200:201], v[44:47], off nt
	global_store_dwordx4 v[200:201], v[40:43], off offset:16 nt
	global_store_dwordx4 v[200:201], v[36:39], off offset:128 nt
	global_store_dwordx4 v[200:201], v[32:35], off offset:144 nt
.Lq_nf_n5:
	v_lshl_add_u64 v[196:197], v[196:197], 0, s[78:79]
	v_lshl_add_u64 v[200:201], v[200:201], 0, s[36:37]
	v_mov_b32_e32 v136, v246
	v_pk_mul_f32 v[28:29], v[28:29], v[136:137] op_sel_hi:[1,0]
	v_pk_mul_f32 v[30:31], v[30:31], v[136:137] op_sel_hi:[1,0]
	v_pk_mul_f32 v[24:25], v[24:25], v[136:137] op_sel_hi:[1,0]
	v_pk_mul_f32 v[26:27], v[26:27], v[136:137] op_sel_hi:[1,0]
	v_pk_mul_f32 v[20:21], v[20:21], v[136:137] op_sel_hi:[1,0]
	v_pk_mul_f32 v[22:23], v[22:23], v[136:137] op_sel_hi:[1,0]
	v_pk_mul_f32 v[16:17], v[16:17], v[136:137] op_sel_hi:[1,0]
	v_pk_mul_f32 v[18:19], v[18:19], v[136:137] op_sel_hi:[1,0]
	v_mul_f32_e32 v168, v29, v29
	v_mul_f32_e32 v169, v31, v31
	v_mul_f32_e32 v170, v25, v25
	v_mul_f32_e32 v171, v27, v27
	v_mul_f32_e32 v172, v21, v21
	v_mul_f32_e32 v173, v23, v23
	v_mul_f32_e32 v174, v17, v17
	v_mul_f32_e32 v175, v19, v19
	v_fmac_f32_e32 v168, v28, v28
	v_fmac_f32_e32 v169, v30, v30
	v_fmac_f32_e32 v170, v24, v24
	v_fmac_f32_e32 v171, v26, v26
	v_fmac_f32_e32 v172, v20, v20
	v_fmac_f32_e32 v173, v22, v22
	v_fmac_f32_e32 v174, v16, v16
	v_fmac_f32_e32 v175, v18, v18
	v_add_f32_e32 v168, v168, v169
	v_add_f32_e32 v170, v170, v171
	v_add_f32_e32 v172, v172, v173
	v_add_f32_e32 v174, v174, v175
	v_add_f32_e32 v168, v168, v170
	v_add_f32_e32 v168, v168, v172
	v_add_f32_e32 v168, v168, v174
	ds_bpermute_b32 v169, v176, v168
	s_waitcnt lgkmcnt(0)
	v_add_f32_e32 v168, v168, v169
	ds_bpermute_b32 v169, v177, v168
	s_waitcnt lgkmcnt(0)
	v_add_f32_e32 v168, v168, v169
	v_fmamk_f32 v168, v168, 0x3c800000, v191
	v_rsq_f32_e32 v136, v168
	s_nop 0
	v_pk_mul_f32 v[28:29], v[28:29], v[136:137] op_sel_hi:[1,0]
	v_pk_mul_f32 v[30:31], v[30:31], v[136:137] op_sel_hi:[1,0]
	v_pk_mul_f32 v[24:25], v[24:25], v[136:137] op_sel_hi:[1,0]
	v_pk_mul_f32 v[26:27], v[26:27], v[136:137] op_sel_hi:[1,0]
	v_pk_mul_f32 v[20:21], v[20:21], v[136:137] op_sel_hi:[1,0]
	v_pk_mul_f32 v[22:23], v[22:23], v[136:137] op_sel_hi:[1,0]
	v_pk_mul_f32 v[16:17], v[16:17], v[136:137] op_sel_hi:[1,0]
	v_pk_mul_f32 v[18:19], v[18:19], v[136:137] op_sel_hi:[1,0]
	v_pk_mul_f32 v[28:29], v[152:153], v[28:29]
	v_pk_mul_f32 v[30:31], v[154:155], v[30:31]
	v_pk_mul_f32 v[24:25], v[156:157], v[24:25]
	v_pk_mul_f32 v[26:27], v[158:159], v[26:27]
	v_pk_mul_f32 v[20:21], v[160:161], v[20:21]
	v_pk_mul_f32 v[22:23], v[162:163], v[22:23]
	v_pk_mul_f32 v[16:17], v[164:165], v[16:17]
	v_pk_mul_f32 v[18:19], v[166:167], v[18:19]
	v_cvt_pk_bf16_f32 v208, v28, v29
	v_cvt_pk_bf16_f32 v209, v30, v31
	v_cvt_pk_bf16_f32 v210, v24, v25
	v_cvt_pk_bf16_f32 v211, v26, v27
	v_cvt_pk_bf16_f32 v212, v20, v21
	v_cvt_pk_bf16_f32 v213, v22, v23
	v_cvt_pk_bf16_f32 v214, v16, v17
	v_cvt_pk_bf16_f32 v215, v18, v19
	global_store_dwordx4 v[196:197], v[208:211], off
	global_store_dwordx4 v[196:197], v[212:215], off offset:64
	s_and_b64 vcc, exec, s[20:21]
	s_cbranch_vccz .Lq_nf_n6
	global_store_dwordx4 v[200:201], v[28:31], off nt
	global_store_dwordx4 v[200:201], v[24:27], off offset:16 nt
	global_store_dwordx4 v[200:201], v[20:23], off offset:128 nt
	global_store_dwordx4 v[200:201], v[16:19], off offset:144 nt
.Lq_nf_n6:
	v_lshl_add_u64 v[196:197], v[196:197], 0, s[76:77]
	v_lshl_add_u64 v[200:201], v[200:201], 0, s[36:37]
	v_mov_b32_e32 v136, v247
	v_pk_mul_f32 v[12:13], v[12:13], v[136:137] op_sel_hi:[1,0]
	v_pk_mul_f32 v[14:15], v[14:15], v[136:137] op_sel_hi:[1,0]
	v_pk_mul_f32 v[8:9], v[8:9], v[136:137] op_sel_hi:[1,0]
	v_pk_mul_f32 v[10:11], v[10:11], v[136:137] op_sel_hi:[1,0]
	v_pk_mul_f32 v[4:5], v[4:5], v[136:137] op_sel_hi:[1,0]
	v_pk_mul_f32 v[6:7], v[6:7], v[136:137] op_sel_hi:[1,0]
	v_pk_mul_f32 v[0:1], v[0:1], v[136:137] op_sel_hi:[1,0]
	v_pk_mul_f32 v[2:3], v[2:3], v[136:137] op_sel_hi:[1,0]
	v_mul_f32_e32 v168, v13, v13
	v_mul_f32_e32 v169, v15, v15
	v_mul_f32_e32 v170, v9, v9
	v_mul_f32_e32 v171, v11, v11
	v_mul_f32_e32 v172, v5, v5
	v_mul_f32_e32 v173, v7, v7
	v_mul_f32_e32 v174, v1, v1
	v_mul_f32_e32 v175, v3, v3
	v_fmac_f32_e32 v168, v12, v12
	v_fmac_f32_e32 v169, v14, v14
	v_fmac_f32_e32 v170, v8, v8
	v_fmac_f32_e32 v171, v10, v10
	v_fmac_f32_e32 v172, v4, v4
	v_fmac_f32_e32 v173, v6, v6
	v_fmac_f32_e32 v174, v0, v0
	v_fmac_f32_e32 v175, v2, v2
	v_add_f32_e32 v168, v168, v169
	v_add_f32_e32 v170, v170, v171
	v_add_f32_e32 v172, v172, v173
	v_add_f32_e32 v174, v174, v175
	v_add_f32_e32 v168, v168, v170
	v_add_f32_e32 v168, v168, v172
	v_add_f32_e32 v168, v168, v174
	ds_bpermute_b32 v169, v176, v168
	s_waitcnt lgkmcnt(0)
	v_add_f32_e32 v168, v168, v169
	ds_bpermute_b32 v169, v177, v168
	s_waitcnt lgkmcnt(0)
	v_add_f32_e32 v168, v168, v169
	v_fmamk_f32 v168, v168, 0x3c800000, v191
	v_rsq_f32_e32 v136, v168
	s_nop 0
	v_pk_mul_f32 v[12:13], v[12:13], v[136:137] op_sel_hi:[1,0]
	v_pk_mul_f32 v[14:15], v[14:15], v[136:137] op_sel_hi:[1,0]
	v_pk_mul_f32 v[8:9], v[8:9], v[136:137] op_sel_hi:[1,0]
	v_pk_mul_f32 v[10:11], v[10:11], v[136:137] op_sel_hi:[1,0]
	v_pk_mul_f32 v[4:5], v[4:5], v[136:137] op_sel_hi:[1,0]
	v_pk_mul_f32 v[6:7], v[6:7], v[136:137] op_sel_hi:[1,0]
	v_pk_mul_f32 v[0:1], v[0:1], v[136:137] op_sel_hi:[1,0]
	v_pk_mul_f32 v[2:3], v[2:3], v[136:137] op_sel_hi:[1,0]
	v_pk_mul_f32 v[12:13], v[152:153], v[12:13]
	v_pk_mul_f32 v[14:15], v[154:155], v[14:15]
	v_pk_mul_f32 v[8:9], v[156:157], v[8:9]
	v_pk_mul_f32 v[10:11], v[158:159], v[10:11]
	v_pk_mul_f32 v[4:5], v[160:161], v[4:5]
	v_pk_mul_f32 v[6:7], v[162:163], v[6:7]
	v_pk_mul_f32 v[0:1], v[164:165], v[0:1]
	v_pk_mul_f32 v[2:3], v[166:167], v[2:3]
	v_cvt_pk_bf16_f32 v208, v12, v13
	v_cvt_pk_bf16_f32 v209, v14, v15
	v_cvt_pk_bf16_f32 v210, v8, v9
	v_cvt_pk_bf16_f32 v211, v10, v11
	v_cvt_pk_bf16_f32 v212, v4, v5
	v_cvt_pk_bf16_f32 v213, v6, v7
	v_cvt_pk_bf16_f32 v214, v0, v1
	v_cvt_pk_bf16_f32 v215, v2, v3
	global_store_dwordx4 v[196:197], v[208:211], off
	global_store_dwordx4 v[196:197], v[212:215], off offset:64
	s_and_b64 vcc, exec, s[20:21]
	s_cbranch_vccz .Lq_nf_n7
	global_store_dwordx4 v[200:201], v[12:15], off nt
	global_store_dwordx4 v[200:201], v[8:11], off offset:16 nt
	global_store_dwordx4 v[200:201], v[4:7], off offset:128 nt
	global_store_dwordx4 v[200:201], v[0:3], off offset:144 nt
.Lq_nf_n7:
	s_branch .Lq_done
.Lq_nonorm:
	v_mov_b32_e32 v136, v240
	v_pk_mul_f32 v[124:125], v[124:125], v[136:137] op_sel_hi:[1,0]
	v_pk_mul_f32 v[126:127], v[126:127], v[136:137] op_sel_hi:[1,0]
	v_pk_mul_f32 v[120:121], v[120:121], v[136:137] op_sel_hi:[1,0]
	v_pk_mul_f32 v[122:123], v[122:123], v[136:137] op_sel_hi:[1,0]
	v_pk_mul_f32 v[116:117], v[116:117], v[136:137] op_sel_hi:[1,0]
	v_pk_mul_f32 v[118:119], v[118:119], v[136:137] op_sel_hi:[1,0]
	v_pk_mul_f32 v[112:113], v[112:113], v[136:137] op_sel_hi:[1,0]
	v_pk_mul_f32 v[114:115], v[114:115], v[136:137] op_sel_hi:[1,0]
	v_cvt_pk_bf16_f32 v208, v124, v125
	v_cvt_pk_bf16_f32 v209, v126, v127
	v_cvt_pk_bf16_f32 v210, v120, v121
	v_cvt_pk_bf16_f32 v211, v122, v123
	v_cvt_pk_bf16_f32 v212, v116, v117
	v_cvt_pk_bf16_f32 v213, v118, v119
	v_cvt_pk_bf16_f32 v214, v112, v113
	v_cvt_pk_bf16_f32 v215, v114, v115
	global_store_dwordx4 v[196:197], v[208:211], off
	global_store_dwordx4 v[196:197], v[212:215], off offset:64
	s_and_b64 vcc, exec, s[20:21]
	s_cbranch_vccz .Lq_nf_p0
	global_store_dwordx4 v[200:201], v[124:127], off nt
	global_store_dwordx4 v[200:201], v[120:123], off offset:16 nt
	global_store_dwordx4 v[200:201], v[116:119], off offset:128 nt
	global_store_dwordx4 v[200:201], v[112:115], off offset:144 nt
.Lq_nf_p0:
	v_lshl_add_u64 v[196:197], v[196:197], 0, s[76:77]
	v_lshl_add_u64 v[200:201], v[200:201], 0, s[36:37]
	v_mov_b32_e32 v136, v241
	v_pk_mul_f32 v[108:109], v[108:109], v[136:137] op_sel_hi:[1,0]
	v_pk_mul_f32 v[110:111], v[110:111], v[136:137] op_sel_hi:[1,0]
	v_pk_mul_f32 v[104:105], v[104:105], v[136:137] op_sel_hi:[1,0]
	v_pk_mul_f32 v[106:107], v[106:107], v[136:137] op_sel_hi:[1,0]
	v_pk_mul_f32 v[100:101], v[100:101], v[136:137] op_sel_hi:[1,0]
	v_pk_mul_f32 v[102:103], v[102:103], v[136:137] op_sel_hi:[1,0]
	v_pk_mul_f32 v[96:97], v[96:97], v[136:137] op_sel_hi:[1,0]
	v_pk_mul_f32 v[98:99], v[98:99], v[136:137] op_sel_hi:[1,0]
	v_cvt_pk_bf16_f32 v208, v108, v109
	v_cvt_pk_bf16_f32 v209, v110, v111
	v_cvt_pk_bf16_f32 v210, v104, v105
	v_cvt_pk_bf16_f32 v211, v106, v107
	v_cvt_pk_bf16_f32 v212, v100, v101
	v_cvt_pk_bf16_f32 v213, v102, v103
	v_cvt_pk_bf16_f32 v214, v96, v97
	v_cvt_pk_bf16_f32 v215, v98, v99
	global_store_dwordx4 v[196:197], v[208:211], off
	global_store_dwordx4 v[196:197], v[212:215], off offset:64
	s_and_b64 vcc, exec, s[20:21]
	s_cbranch_vccz .Lq_nf_p1
	global_store_dwordx4 v[200:201], v[108:111], off nt
	global_store_dwordx4 v[200:201], v[104:107], off offset:16 nt
	global_store_dwordx4 v[200:201], v[100:103], off offset:128 nt
	global_store_dwordx4 v[200:201], v[96:99], off offset:144 nt
.Lq_nf_p1:
	v_lshl_add_u64 v[196:197], v[196:197], 0, s[78:79]
	v_lshl_add_u64 v[200:201], v[200:201], 0, s[36:37]
	v_mov_b32_e32 v136, v242
	v_pk_mul_f32 v[92:93], v[92:93], v[136:137] op_sel_hi:[1,0]
	v_pk_mul_f32 v[94:95], v[94:95], v[136:137] op_sel_hi:[1,0]
	v_pk_mul_f32 v[88:89], v[88:89], v[136:137] op_sel_hi:[1,0]
	v_pk_mul_f32 v[90:91], v[90:91], v[136:137] op_sel_hi:[1,0]
	v_pk_mul_f32 v[84:85], v[84:85], v[136:137] op_sel_hi:[1,0]
	v_pk_mul_f32 v[86:87], v[86:87], v[136:137] op_sel_hi:[1,0]
	v_pk_mul_f32 v[80:81], v[80:81], v[136:137] op_sel_hi:[1,0]
	v_pk_mul_f32 v[82:83], v[82:83], v[136:137] op_sel_hi:[1,0]
	v_cvt_pk_bf16_f32 v208, v92, v93
	v_cvt_pk_bf16_f32 v209, v94, v95
	v_cvt_pk_bf16_f32 v210, v88, v89
	v_cvt_pk_bf16_f32 v211, v90, v91
	v_cvt_pk_bf16_f32 v212, v84, v85
	v_cvt_pk_bf16_f32 v213, v86, v87
	v_cvt_pk_bf16_f32 v214, v80, v81
	v_cvt_pk_bf16_f32 v215, v82, v83
	global_store_dwordx4 v[196:197], v[208:211], off
	global_store_dwordx4 v[196:197], v[212:215], off offset:64
	s_and_b64 vcc, exec, s[20:21]
	s_cbranch_vccz .Lq_nf_p2
	global_store_dwordx4 v[200:201], v[92:95], off nt
	global_store_dwordx4 v[200:201], v[88:91], off offset:16 nt
	global_store_dwordx4 v[200:201], v[84:87], off offset:128 nt
	global_store_dwordx4 v[200:201], v[80:83], off offset:144 nt
.Lq_nf_p2:
	v_lshl_add_u64 v[196:197], v[196:197], 0, s[76:77]
	v_lshl_add_u64 v[200:201], v[200:201], 0, s[36:37]
	v_mov_b32_e32 v136, v243
	v_pk_mul_f32 v[76:77], v[76:77], v[136:137] op_sel_hi:[1,0]
	v_pk_mul_f32 v[78:79], v[78:79], v[136:137] op_sel_hi:[1,0]
	v_pk_mul_f32 v[72:73], v[72:73], v[136:137] op_sel_hi:[1,0]
	v_pk_mul_f32 v[74:75], v[74:75], v[136:137] op_sel_hi:[1,0]
	v_pk_mul_f32 v[68:69], v[68:69], v[136:137] op_sel_hi:[1,0]
	v_pk_mul_f32 v[70:71], v[70:71], v[136:137] op_sel_hi:[1,0]
	v_pk_mul_f32 v[64:65], v[64:65], v[136:137] op_sel_hi:[1,0]
	v_pk_mul_f32 v[66:67], v[66:67], v[136:137] op_sel_hi:[1,0]
	v_cvt_pk_bf16_f32 v208, v76, v77
	v_cvt_pk_bf16_f32 v209, v78, v79
	v_cvt_pk_bf16_f32 v210, v72, v73
	v_cvt_pk_bf16_f32 v211, v74, v75
	v_cvt_pk_bf16_f32 v212, v68, v69
	v_cvt_pk_bf16_f32 v213, v70, v71
	v_cvt_pk_bf16_f32 v214, v64, v65
	v_cvt_pk_bf16_f32 v215, v66, v67
	global_store_dwordx4 v[196:197], v[208:211], off
	global_store_dwordx4 v[196:197], v[212:215], off offset:64
	s_and_b64 vcc, exec, s[20:21]
	s_cbranch_vccz .Lq_nf_p3
	global_store_dwordx4 v[200:201], v[76:79], off nt
	global_store_dwordx4 v[200:201], v[72:75], off offset:16 nt
	global_store_dwordx4 v[200:201], v[68:71], off offset:128 nt
	global_store_dwordx4 v[200:201], v[64:67], off offset:144 nt
.Lq_nf_p3:
	v_lshl_add_u64 v[196:197], v[196:197], 0, s[70:71]
	v_lshl_add_u64 v[200:201], v[200:201], 0, s[50:51]
	v_mov_b32_e32 v136, v244
	v_pk_mul_f32 v[60:61], v[60:61], v[136:137] op_sel_hi:[1,0]
	v_pk_mul_f32 v[62:63], v[62:63], v[136:137] op_sel_hi:[1,0]
	v_pk_mul_f32 v[56:57], v[56:57], v[136:137] op_sel_hi:[1,0]
	v_pk_mul_f32 v[58:59], v[58:59], v[136:137] op_sel_hi:[1,0]
	v_pk_mul_f32 v[52:53], v[52:53], v[136:137] op_sel_hi:[1,0]
	v_pk_mul_f32 v[54:55], v[54:55], v[136:137] op_sel_hi:[1,0]
	v_pk_mul_f32 v[48:49], v[48:49], v[136:137] op_sel_hi:[1,0]
	v_pk_mul_f32 v[50:51], v[50:51], v[136:137] op_sel_hi:[1,0]
	v_cvt_pk_bf16_f32 v208, v60, v61
	v_cvt_pk_bf16_f32 v209, v62, v63
	v_cvt_pk_bf16_f32 v210, v56, v57
	v_cvt_pk_bf16_f32 v211, v58, v59
	v_cvt_pk_bf16_f32 v212, v52, v53
	v_cvt_pk_bf16_f32 v213, v54, v55
	v_cvt_pk_bf16_f32 v214, v48, v49
	v_cvt_pk_bf16_f32 v215, v50, v51
	global_store_dwordx4 v[196:197], v[208:211], off
	global_store_dwordx4 v[196:197], v[212:215], off offset:64
	s_and_b64 vcc, exec, s[20:21]
	s_cbranch_vccz .Lq_nf_p4
	global_store_dwordx4 v[200:201], v[60:63], off nt
	global_store_dwordx4 v[200:201], v[56:59], off offset:16 nt
	global_store_dwordx4 v[200:201], v[52:55], off offset:128 nt
	global_store_dwordx4 v[200:201], v[48:51], off offset:144 nt
.Lq_nf_p4:
	v_lshl_add_u64 v[196:197], v[196:197], 0, s[76:77]
	v_lshl_add_u64 v[200:201], v[200:201], 0, s[36:37]
	v_mov_b32_e32 v136, v245
	v_pk_mul_f32 v[44:45], v[44:45], v[136:137] op_sel_hi:[1,0]
	v_pk_mul_f32 v[46:47], v[46:47], v[136:137] op_sel_hi:[1,0]
	v_pk_mul_f32 v[40:41], v[40:41], v[136:137] op_sel_hi:[1,0]
	v_pk_mul_f32 v[42:43], v[42:43], v[136:137] op_sel_hi:[1,0]
	v_pk_mul_f32 v[36:37], v[36:37], v[136:137] op_sel_hi:[1,0]
	v_pk_mul_f32 v[38:39], v[38:39], v[136:137] op_sel_hi:[1,0]
	v_pk_mul_f32 v[32:33], v[32:33], v[136:137] op_sel_hi:[1,0]
	v_pk_mul_f32 v[34:35], v[34:35], v[136:137] op_sel_hi:[1,0]
	v_cvt_pk_bf16_f32 v208, v44, v45
	v_cvt_pk_bf16_f32 v209, v46, v47
	v_cvt_pk_bf16_f32 v210, v40, v41
	v_cvt_pk_bf16_f32 v211, v42, v43
	v_cvt_pk_bf16_f32 v212, v36, v37
	v_cvt_pk_bf16_f32 v213, v38, v39
	v_cvt_pk_bf16_f32 v214, v32, v33
	v_cvt_pk_bf16_f32 v215, v34, v35
	global_store_dwordx4 v[196:197], v[208:211], off
	global_store_dwordx4 v[196:197], v[212:215], off offset:64
	s_and_b64 vcc, exec, s[20:21]
	s_cbranch_vccz .Lq_nf_p5
	global_store_dwordx4 v[200:201], v[44:47], off nt
	global_store_dwordx4 v[200:201], v[40:43], off offset:16 nt
	global_store_dwordx4 v[200:201], v[36:39], off offset:128 nt
	global_store_dwordx4 v[200:201], v[32:35], off offset:144 nt
.Lq_nf_p5:
	v_lshl_add_u64 v[196:197], v[196:197], 0, s[78:79]
	v_lshl_add_u64 v[200:201], v[200:201], 0, s[36:37]
	v_mov_b32_e32 v136, v246
	v_pk_mul_f32 v[28:29], v[28:29], v[136:137] op_sel_hi:[1,0]
	v_pk_mul_f32 v[30:31], v[30:31], v[136:137] op_sel_hi:[1,0]
	v_pk_mul_f32 v[24:25], v[24:25], v[136:137] op_sel_hi:[1,0]
	v_pk_mul_f32 v[26:27], v[26:27], v[136:137] op_sel_hi:[1,0]
	v_pk_mul_f32 v[20:21], v[20:21], v[136:137] op_sel_hi:[1,0]
	v_pk_mul_f32 v[22:23], v[22:23], v[136:137] op_sel_hi:[1,0]
	v_pk_mul_f32 v[16:17], v[16:17], v[136:137] op_sel_hi:[1,0]
	v_pk_mul_f32 v[18:19], v[18:19], v[136:137] op_sel_hi:[1,0]
	v_cvt_pk_bf16_f32 v208, v28, v29
	v_cvt_pk_bf16_f32 v209, v30, v31
	v_cvt_pk_bf16_f32 v210, v24, v25
	v_cvt_pk_bf16_f32 v211, v26, v27
	v_cvt_pk_bf16_f32 v212, v20, v21
	v_cvt_pk_bf16_f32 v213, v22, v23
	v_cvt_pk_bf16_f32 v214, v16, v17
	v_cvt_pk_bf16_f32 v215, v18, v19
	global_store_dwordx4 v[196:197], v[208:211], off
	global_store_dwordx4 v[196:197], v[212:215], off offset:64
	s_and_b64 vcc, exec, s[20:21]
	s_cbranch_vccz .Lq_nf_p6
	global_store_dwordx4 v[200:201], v[28:31], off nt
	global_store_dwordx4 v[200:201], v[24:27], off offset:16 nt
	global_store_dwordx4 v[200:201], v[20:23], off offset:128 nt
	global_store_dwordx4 v[200:201], v[16:19], off offset:144 nt
.Lq_nf_p6:
	v_lshl_add_u64 v[196:197], v[196:197], 0, s[76:77]
	v_lshl_add_u64 v[200:201], v[200:201], 0, s[36:37]
	v_mov_b32_e32 v136, v247
	v_pk_mul_f32 v[12:13], v[12:13], v[136:137] op_sel_hi:[1,0]
	v_pk_mul_f32 v[14:15], v[14:15], v[136:137] op_sel_hi:[1,0]
	v_pk_mul_f32 v[8:9], v[8:9], v[136:137] op_sel_hi:[1,0]
	v_pk_mul_f32 v[10:11], v[10:11], v[136:137] op_sel_hi:[1,0]
	v_pk_mul_f32 v[4:5], v[4:5], v[136:137] op_sel_hi:[1,0]
	v_pk_mul_f32 v[6:7], v[6:7], v[136:137] op_sel_hi:[1,0]
	v_pk_mul_f32 v[0:1], v[0:1], v[136:137] op_sel_hi:[1,0]
	v_pk_mul_f32 v[2:3], v[2:3], v[136:137] op_sel_hi:[1,0]
	v_cvt_pk_bf16_f32 v208, v12, v13
	v_cvt_pk_bf16_f32 v209, v14, v15
	v_cvt_pk_bf16_f32 v210, v8, v9
	v_cvt_pk_bf16_f32 v211, v10, v11
	v_cvt_pk_bf16_f32 v212, v4, v5
	v_cvt_pk_bf16_f32 v213, v6, v7
	v_cvt_pk_bf16_f32 v214, v0, v1
	v_cvt_pk_bf16_f32 v215, v2, v3
	global_store_dwordx4 v[196:197], v[208:211], off
	global_store_dwordx4 v[196:197], v[212:215], off offset:64
	s_and_b64 vcc, exec, s[20:21]
	s_cbranch_vccz .Lq_nf_p7
	global_store_dwordx4 v[200:201], v[12:15], off nt
	global_store_dwordx4 v[200:201], v[8:11], off offset:16 nt
	global_store_dwordx4 v[200:201], v[4:7], off offset:128 nt
	global_store_dwordx4 v[200:201], v[0:3], off offset:144 nt
.Lq_nf_p7:
.Lq_done:
	s_and_b64 vcc, exec, s[2:3]
	s_cbranch_vccz .Lp1_nonext
	s_lshl_b32 s4, s44, 8
	v_add_u32_e32 v248, s4, v141
	v_mov_b32_e32 v249, 0
	v_lshl_add_u64 v[248:249], v[248:249], 2, s[18:19]
	global_load_dword v240, v[248:249], off
	global_load_dword v241, v[248:249], off offset:64
	global_load_dword v242, v[248:249], off offset:128
	global_load_dword v243, v[248:249], off offset:192
	global_load_dword v244, v[248:249], off offset:512
	global_load_dword v245, v[248:249], off offset:576
	global_load_dword v246, v[248:249], off offset:640
	global_load_dword v247, v[248:249], off offset:704
